# gdn_prep block solve: all T/L fragments preloaded once (one LDS round trip instead of eight) for both column tiles
# speedup vs baseline: 1.0111x; 1.0035x over previous
; DI void phase_gdn_prep(const Params& p, int l, char* smem) {
;     ...
;             if (tid < 128) {
;                 float* X = (tid < 64) ? sv : sk; const int col = tid & 63;
;                 float x[16];
; #pragma unroll
;                 for (int i = 0; i < 16; ++i) x[i] = X[(rb * 16 + i) * 65 + col];
; #pragma unroll
;                 for (int i = 1; i < 16; ++i) {
;                     const float* Lr = sL + (rb * 16 + i) * 64 + rb * 16;
;                     float acc = x[i];
; #pragma unroll
;                     for (int s2 = 0; s2 < i; ++s2) acc -= Lr[s2] * x[s2];
;                     x[i] = acc;
;                 }
; #pragma unroll
;                 for (int i = 1; i < 16; ++i) X[(rb * 16 + i) * 65 + col] = x[i];
.LBB0_333:
	s_or_b64 exec, exec, s[4:5]
	v_lshrrev_b32_e32 v185, 6, v40
	v_and_b32_e32 v191, 15, v62
	v_lshrrev_b32_e32 v208, 4, v62
	v_mul_u32_u24_e32 v186, 0x1040, v185
	v_lshl_add_u32 v186, v191, 2, v186
	v_add_u32_e32 v186, 0xc300, v186
	ds_read_b32 v36, v186 offset:256
	ds_read_b32 v37, v186 offset:512
	ds_read_b32 v38, v186 offset:768
	ds_read_b32 v39, v186 offset:1024
	ds_read_b32 v58, v186 offset:1280
	ds_read_b32 v59, v186 offset:1536
	ds_read_b32 v60, v186 offset:1792
	ds_read_b32 v61, v186 offset:2048
	ds_read_b32 v230, v186 offset:2304
	ds_read_b32 v231, v186 offset:2560
	ds_read_b32 v232, v186 offset:2816
	ds_read_b32 v233, v186 offset:3072
	ds_read_b32 v234, v186 offset:3328
	ds_read_b32 v235, v186 offset:3584
	ds_read_b32 v236, v186 offset:3840
	v_cmp_eq_u32_e64 s[4:5], 0, v191
	v_cmp_eq_u32_e64 s[6:7], 1, v191
	v_cmp_eq_u32_e64 s[86:87], 2, v191
	v_cndmask_b32_e64 v192, 0, 1.0, s[4:5]
	v_cmp_eq_u32_e64 s[4:5], 3, v191
	v_cndmask_b32_e64 v193, 0, 1.0, s[6:7]
	v_cmp_eq_u32_e64 s[6:7], 4, v191
	v_cndmask_b32_e64 v194, 0, 1.0, s[86:87]
	v_cmp_eq_u32_e64 s[86:87], 5, v191
	v_cndmask_b32_e64 v195, 0, 1.0, s[4:5]
	v_cmp_eq_u32_e64 s[4:5], 6, v191
	v_cndmask_b32_e64 v196, 0, 1.0, s[6:7]
	v_cmp_eq_u32_e64 s[6:7], 7, v191
	v_cndmask_b32_e64 v197, 0, 1.0, s[86:87]
	v_cmp_eq_u32_e64 s[86:87], 8, v191
	v_cndmask_b32_e64 v198, 0, 1.0, s[4:5]
	v_cmp_eq_u32_e64 s[4:5], 9, v191
	v_cndmask_b32_e64 v199, 0, 1.0, s[6:7]
	v_cmp_eq_u32_e64 s[6:7], 10, v191
	v_cndmask_b32_e64 v200, 0, 1.0, s[86:87]
	v_cmp_eq_u32_e64 s[86:87], 11, v191
	v_cndmask_b32_e64 v201, 0, 1.0, s[4:5]
	v_cmp_eq_u32_e64 s[4:5], 12, v191
	v_cndmask_b32_e64 v202, 0, 1.0, s[6:7]
	v_cmp_eq_u32_e64 s[6:7], 13, v191
	v_cndmask_b32_e64 v203, 0, 1.0, s[86:87]
	v_cmp_eq_u32_e64 s[86:87], 14, v191
	v_cndmask_b32_e64 v204, 0, 1.0, s[4:5]
	v_cmp_eq_u32_e64 s[4:5], 15, v191
	v_cndmask_b32_e64 v205, 0, 1.0, s[6:7]
	v_cndmask_b32_e64 v206, 0, 1.0, s[86:87]
	v_cndmask_b32_e64 v207, 0, 1.0, s[4:5]
	s_waitcnt lgkmcnt(0)
	s_nop 1
	v_readlane_b32 s98, v36, 0
	v_readlane_b32 s99, v37, 0
	v_readlane_b32 s100, v37, 1
	v_readlane_b32 s101, v38, 0
	v_fma_f32 v193, -v192, s98, v193
	v_readlane_b32 s6, v39, 0
	v_fma_f32 v194, -v192, s99, v194
	v_readlane_b32 s7, v38, 1
	v_fma_f32 v194, -v193, s100, v194
	v_readlane_b32 s98, v39, 1
	v_fma_f32 v195, -v192, s101, v195
	v_readlane_b32 s99, v38, 2
	v_fma_f32 v196, -v192, s6, v196
	v_readlane_b32 s100, v39, 2
	v_fma_f32 v195, -v193, s7, v195
	v_readlane_b32 s101, v39, 3
	v_fma_f32 v196, -v193, s98, v196
	v_readlane_b32 s6, v58, 0
	v_fma_f32 v195, -v194, s99, v195
	v_readlane_b32 s7, v59, 0
	v_fma_f32 v196, -v194, s100, v196
	v_readlane_b32 s98, v58, 1
	v_fma_f32 v196, -v195, s101, v196
	v_readlane_b32 s99, v59, 1
	v_fma_f32 v197, -v192, s6, v197
	v_readlane_b32 s100, v58, 2
	v_fma_f32 v198, -v192, s7, v198
	v_readlane_b32 s101, v59, 2
	v_fma_f32 v197, -v193, s98, v197
	v_readlane_b32 s6, v58, 3
	v_fma_f32 v198, -v193, s99, v198
	v_readlane_b32 s7, v59, 3
	v_fma_f32 v197, -v194, s100, v197
	v_readlane_b32 s98, v58, 4
	v_fma_f32 v198, -v194, s101, v198
	v_readlane_b32 s99, v59, 4
	v_fma_f32 v197, -v195, s6, v197
	v_readlane_b32 s100, v59, 5
	v_fma_f32 v198, -v195, s7, v198
	v_readlane_b32 s101, v60, 0
	v_fma_f32 v197, -v196, s98, v197
	v_readlane_b32 s6, v61, 0
	v_fma_f32 v198, -v196, s99, v198
	v_readlane_b32 s7, v60, 1
	v_fma_f32 v198, -v197, s100, v198
	v_readlane_b32 s98, v61, 1
	v_fma_f32 v199, -v192, s101, v199
	v_readlane_b32 s99, v60, 2
	v_fma_f32 v200, -v192, s6, v200
	v_readlane_b32 s100, v61, 2
	v_fma_f32 v199, -v193, s7, v199
	v_readlane_b32 s101, v60, 3
	v_fma_f32 v200, -v193, s98, v200
	v_readlane_b32 s6, v61, 3
	v_fma_f32 v199, -v194, s99, v199
	v_readlane_b32 s7, v60, 4
	v_fma_f32 v200, -v194, s100, v200
	v_readlane_b32 s98, v61, 4
	v_fma_f32 v199, -v195, s101, v199
	v_readlane_b32 s99, v60, 5
	v_fma_f32 v200, -v195, s6, v200
	v_readlane_b32 s100, v61, 5
	v_fma_f32 v199, -v196, s7, v199
	v_readlane_b32 s101, v60, 6
	v_fma_f32 v200, -v196, s98, v200
	v_readlane_b32 s6, v61, 6
	v_fma_f32 v199, -v197, s99, v199
	v_readlane_b32 s7, v61, 7
	v_fma_f32 v200, -v197, s100, v200
	v_readlane_b32 s98, v230, 0
	v_fma_f32 v199, -v198, s101, v199
	v_readlane_b32 s99, v231, 0
	v_fma_f32 v200, -v198, s6, v200
	v_readlane_b32 s100, v230, 1
	v_fma_f32 v200, -v199, s7, v200
	v_readlane_b32 s101, v231, 1
	v_fma_f32 v201, -v192, s98, v201
	v_readlane_b32 s6, v230, 2
	v_fma_f32 v202, -v192, s99, v202
	v_readlane_b32 s7, v231, 2
	v_fma_f32 v201, -v193, s100, v201
	v_readlane_b32 s98, v230, 3
	v_fma_f32 v202, -v193, s101, v202
	v_readlane_b32 s99, v231, 3
	v_fma_f32 v201, -v194, s6, v201
	v_readlane_b32 s100, v230, 4
	v_fma_f32 v202, -v194, s7, v202
	v_readlane_b32 s101, v231, 4
	v_fma_f32 v201, -v195, s98, v201
	v_readlane_b32 s6, v230, 5
	v_fma_f32 v202, -v195, s99, v202
	v_readlane_b32 s7, v231, 5
	v_fma_f32 v201, -v196, s100, v201
	v_readlane_b32 s98, v230, 6
	v_fma_f32 v202, -v196, s101, v202
	v_readlane_b32 s99, v231, 6
	v_fma_f32 v201, -v197, s6, v201
	v_readlane_b32 s100, v230, 7
	v_fma_f32 v202, -v197, s7, v202
	v_readlane_b32 s101, v231, 7
	v_fma_f32 v201, -v198, s98, v201
	v_readlane_b32 s6, v230, 8
	v_fma_f32 v202, -v198, s99, v202
	v_readlane_b32 s7, v231, 8
	v_fma_f32 v201, -v199, s100, v201
	v_readlane_b32 s98, v231, 9
	v_fma_f32 v202, -v199, s101, v202
	v_readlane_b32 s99, v232, 0
	v_fma_f32 v201, -v200, s6, v201
	v_readlane_b32 s100, v233, 0
	v_fma_f32 v202, -v200, s7, v202
	v_readlane_b32 s101, v232, 1
	v_fma_f32 v202, -v201, s98, v202
	v_readlane_b32 s6, v233, 1
	v_fma_f32 v203, -v192, s99, v203
	v_readlane_b32 s7, v232, 2
	v_fma_f32 v204, -v192, s100, v204
; DI void phase_gdn_prep(const Params& p, int l, char* smem) {
;     ...
;             if (tid < 128) {
;                 float* X = (tid < 64) ? sv : sk; const int col = tid & 63;
;                 float x[16];
; #pragma unroll
;                 for (int i = 0; i < 16; ++i) x[i] = X[(rb * 16 + i) * 65 + col];
; #pragma unroll
;                 for (int i = 1; i < 16; ++i) {
;                     const float* Lr = sL + (rb * 16 + i) * 64 + rb * 16;
;                     float acc = x[i];
; #pragma unroll
;                     for (int s2 = 0; s2 < i; ++s2) acc -= Lr[s2] * x[s2];
;                     x[i] = acc;
;                 }
; #pragma unroll
;                 for (int i = 1; i < 16; ++i) X[(rb * 16 + i) * 65 + col] = x[i];
	v_readlane_b32 s98, v233, 2
	v_fma_f32 v203, -v193, s101, v203
	v_readlane_b32 s99, v232, 3
	v_fma_f32 v204, -v193, s6, v204
	v_readlane_b32 s100, v233, 3
	v_fma_f32 v203, -v194, s7, v203
	v_readlane_b32 s101, v232, 4
	v_fma_f32 v204, -v194, s98, v204
	v_readlane_b32 s6, v233, 4
	v_fma_f32 v203, -v195, s99, v203
	v_readlane_b32 s7, v232, 5
	v_fma_f32 v204, -v195, s100, v204
	v_readlane_b32 s98, v233, 5
	v_fma_f32 v203, -v196, s101, v203
	v_readlane_b32 s99, v232, 6
	v_fma_f32 v204, -v196, s6, v204
	v_readlane_b32 s100, v233, 6
	v_fma_f32 v203, -v197, s7, v203
	v_readlane_b32 s101, v232, 7
	v_fma_f32 v204, -v197, s98, v204
	v_readlane_b32 s6, v233, 7
	v_fma_f32 v203, -v198, s99, v203
	v_readlane_b32 s7, v232, 8
	v_fma_f32 v204, -v198, s100, v204
	v_readlane_b32 s98, v233, 8
	v_fma_f32 v203, -v199, s101, v203
	v_readlane_b32 s99, v232, 9
	v_fma_f32 v204, -v199, s6, v204
	v_readlane_b32 s100, v233, 9
	v_fma_f32 v203, -v200, s7, v203
	v_readlane_b32 s101, v232, 10
	v_fma_f32 v204, -v200, s98, v204
	v_readlane_b32 s6, v233, 10
	v_fma_f32 v203, -v201, s99, v203
	v_readlane_b32 s7, v233, 11
	v_fma_f32 v204, -v201, s100, v204
	v_readlane_b32 s98, v234, 0
	v_fma_f32 v203, -v202, s101, v203
	v_readlane_b32 s99, v235, 0
	v_fma_f32 v204, -v202, s6, v204
	v_readlane_b32 s100, v234, 1
	v_fma_f32 v204, -v203, s7, v204
	v_readlane_b32 s101, v235, 1
	v_fma_f32 v205, -v192, s98, v205
	v_readlane_b32 s6, v234, 2
	v_fma_f32 v206, -v192, s99, v206
	v_readlane_b32 s7, v235, 2
	v_fma_f32 v205, -v193, s100, v205
	v_readlane_b32 s98, v234, 3
	v_fma_f32 v206, -v193, s101, v206
	v_readlane_b32 s99, v235, 3
	v_fma_f32 v205, -v194, s6, v205
	v_readlane_b32 s100, v234, 4
	v_fma_f32 v206, -v194, s7, v206
	v_readlane_b32 s101, v235, 4
	v_fma_f32 v205, -v195, s98, v205
	v_readlane_b32 s6, v234, 5
	v_fma_f32 v206, -v195, s99, v206
	v_readlane_b32 s7, v235, 5
	v_fma_f32 v205, -v196, s100, v205
	v_readlane_b32 s98, v234, 6
	v_fma_f32 v206, -v196, s101, v206
	v_readlane_b32 s99, v235, 6
	v_fma_f32 v205, -v197, s6, v205
	v_readlane_b32 s100, v234, 7
	v_fma_f32 v206, -v197, s7, v206
	v_readlane_b32 s101, v235, 7
	v_fma_f32 v205, -v198, s98, v205
	v_readlane_b32 s6, v234, 8
	v_fma_f32 v206, -v198, s99, v206
	v_readlane_b32 s7, v235, 8
	v_fma_f32 v205, -v199, s100, v205
	v_readlane_b32 s98, v234, 9
	v_fma_f32 v206, -v199, s101, v206
	v_readlane_b32 s99, v235, 9
	v_fma_f32 v205, -v200, s6, v205
	v_readlane_b32 s100, v234, 10
	v_fma_f32 v206, -v200, s7, v206
	v_readlane_b32 s101, v235, 10
	v_fma_f32 v205, -v201, s98, v205
	v_readlane_b32 s6, v234, 11
	v_fma_f32 v206, -v201, s99, v206
	v_readlane_b32 s7, v235, 11
	v_fma_f32 v205, -v202, s100, v205
	v_readlane_b32 s98, v234, 12
	v_fma_f32 v206, -v202, s101, v206
	v_readlane_b32 s99, v235, 12
	v_fma_f32 v205, -v203, s6, v205
	v_readlane_b32 s100, v235, 13
	v_fma_f32 v206, -v203, s7, v206
	v_readlane_b32 s101, v236, 0
	v_fma_f32 v205, -v204, s98, v205
	v_readlane_b32 s6, v236, 1
	v_fma_f32 v206, -v204, s99, v206
	v_readlane_b32 s7, v236, 2
	v_fma_f32 v206, -v205, s100, v206
	v_readlane_b32 s98, v236, 3
	v_fma_f32 v207, -v192, s101, v207
	v_readlane_b32 s99, v236, 4
	v_fma_f32 v207, -v193, s6, v207
	v_readlane_b32 s100, v236, 5
	v_fma_f32 v207, -v194, s7, v207
	v_readlane_b32 s101, v236, 6
	v_fma_f32 v207, -v195, s98, v207
	v_readlane_b32 s6, v236, 7
	v_fma_f32 v207, -v196, s99, v207
	v_readlane_b32 s7, v236, 8
	v_fma_f32 v207, -v197, s100, v207
	v_readlane_b32 s98, v236, 9
	v_fma_f32 v207, -v198, s101, v207
	v_readlane_b32 s99, v236, 10
	v_fma_f32 v207, -v199, s6, v207
	v_readlane_b32 s100, v236, 11
	v_fma_f32 v207, -v200, s7, v207
	v_readlane_b32 s101, v236, 12
	v_fma_f32 v207, -v201, s98, v207
	v_readlane_b32 s6, v236, 13
	v_fma_f32 v207, -v202, s99, v207
	v_readlane_b32 s7, v236, 14
	v_fma_f32 v207, -v203, s100, v207
	v_fma_f32 v207, -v204, s101, v207
	v_fma_f32 v207, -v205, s6, v207
	v_fma_f32 v207, -v206, s7, v207
	v_lshlrev_b32_e32 v186, 10, v185
	v_lshl_add_u32 v186, v191, 2, v186
	ds_write_b32 v186, v192 offset:0
	ds_write_b32 v186, v193 offset:64
	ds_write_b32 v186, v194 offset:128
	ds_write_b32 v186, v195 offset:192
	ds_write_b32 v186, v196 offset:256
	ds_write_b32 v186, v197 offset:320
	ds_write_b32 v186, v198 offset:384
	ds_write_b32 v186, v199 offset:448
	ds_write_b32 v186, v200 offset:512
	ds_write_b32 v186, v201 offset:576
	ds_write_b32 v186, v202 offset:640
	ds_write_b32 v186, v203 offset:704
	ds_write_b32 v186, v204 offset:768
	ds_write_b32 v186, v205 offset:832
	ds_write_b32 v186, v206 offset:896
	ds_write_b32 v186, v207 offset:960
	v_lshlrev_b32_e32 v188, 6, v191
	v_lshl_add_u32 v188, v208, 4, v188
	v_lshlrev_b32_e32 v209, 8, v191
	v_lshl_add_u32 v209, v208, 4, v209
	v_add_u32_e32 v209, 0xc300, v209
	v_mul_u32_u24_e32 v187, 0x410, v208
	v_lshl_add_u32 v187, v191, 2, v187
	v_and_b32_e32 v243, 64, v40
	v_lshl_add_u32 v187, v243, 1, v187
	v_mov_b32_e32 v243, 0x8200
	v_mov_b32_e32 v244, 0x4100
	s_nop 0
	v_cndmask_b32_e64 v243, v244, v243, s[48:49]
	v_add_u32_e32 v187, v187, v243
	s_waitcnt lgkmcnt(0)
	s_barrier
; DI void phase_gdn_prep(const Params& p, int l, char* smem) {
;     ...
;         for (int rb = 0; rb < 4; ++rb) {
;             if (rb > 0) {
;                 const int j = tid & 127, rh = tid >> 7;
;                 float* X = (j < 64) ? sv : sk; const int col = j & 63;
;                 const int r0 = rb * 16 + rh * 8;
;                 float a[8];
; #pragma unroll
;                 for (int i = 0; i < 8; ++i) a[i] = 0.f;
;                 for (int s4 = 0; s4 < rb * 16; s4 += 4) {
;                     const float x0 = X[(s4 + 0) * 65 + col], x1 = X[(s4 + 1) * 65 + col], x2 = X[(s4 + 2) * 65 + col], x3 = X[(s4 + 3) * 65 + col];
; #pragma unroll
;                     for (int i = 0; i < 8; ++i) {
;                         const f32x4 lv = *(const f32x4*)(sL + (r0 + i) * 64 + s4);
;                         a[i] += lv[0] * x0 + lv[1] * x1 + lv[2] * x2 + lv[3] * x3;
;                     }
;                 }
; #pragma unroll
;                 for (int i = 0; i < 8; ++i) X[(r0 + i) * 65 + col] -= a[i];
;                 __syncthreads();
;             }
;             if (tid < 128) {
;                 float* X = (tid < 64) ? sv : sk; const int col = tid & 63;
;                 float x[16];
; #pragma unroll
;                 for (int i = 0; i < 16; ++i) x[i] = X[(rb * 16 + i) * 65 + col];
; #pragma unroll
;                 for (int i = 1; i < 16; ++i) {
;                     const float* Lr = sL + (rb * 16 + i) * 64 + rb * 16;
;                     float acc = x[i];
; #pragma unroll
;                     for (int s2 = 0; s2 < i; ++s2) acc -= Lr[s2] * x[s2];
;                     x[i] = acc;
;                 }
; #pragma unroll
;                 for (int i = 1; i < 16; ++i) X[(rb * 16 + i) * 65 + col] = x[i];
;             }
;             __syncthreads();
;         }
	ds_read_b128 v[36:39], v188 offset:0
	ds_read_b128 v[58:61], v188 offset:1024
	ds_read_b128 v[234:237], v188 offset:2048
	ds_read_b128 v[238:241], v188 offset:3072
	ds_read_b128 v[84:87], v209 offset:4096
	ds_read_b128 v[88:91], v209 offset:8192
	ds_read_b128 v[92:95], v209 offset:8256
	ds_read_b128 v[96:99], v209 offset:12288
	ds_read_b128 v[100:103], v209 offset:12352
	ds_read_b128 v[104:107], v209 offset:12416
	s_waitcnt lgkmcnt(0)
	ds_read_b32 v192, v187 offset:0
	ds_read_b32 v193, v187 offset:260
	ds_read_b32 v194, v187 offset:520
	ds_read_b32 v195, v187 offset:780
	ds_read_b32 v196, v187 offset:4160
	ds_read_b32 v197, v187 offset:4420
	ds_read_b32 v198, v187 offset:4680
	ds_read_b32 v199, v187 offset:4940
	ds_read_b32 v200, v187 offset:8320
	ds_read_b32 v201, v187 offset:8580
	ds_read_b32 v202, v187 offset:8840
	ds_read_b32 v203, v187 offset:9100
	ds_read_b32 v204, v187 offset:12480
	ds_read_b32 v205, v187 offset:12740
	ds_read_b32 v206, v187 offset:13000
	ds_read_b32 v207, v187 offset:13260
	s_waitcnt lgkmcnt(0)
	v_mfma_f32_16x16x4_f32 v[230:233], v36, v192, 0
	v_mfma_f32_16x16x4_f32 v[230:233], v37, v193, v[230:233]
	v_mfma_f32_16x16x4_f32 v[230:233], v38, v194, v[230:233]
	v_mfma_f32_16x16x4_f32 v[230:233], v39, v195, v[230:233]
	s_nop 7
	s_nop 2
	v_mov_b32_e32 v192, v230
	v_mov_b32_e32 v193, v231
	v_mov_b32_e32 v194, v232
	v_mov_b32_e32 v195, v233
	s_nop 7
	s_nop 2
	v_mfma_f32_16x16x4_f32 v[230:233], v84, v192, 0
	v_mfma_f32_16x16x4_f32 v[230:233], v85, v193, v[230:233]
	v_mfma_f32_16x16x4_f32 v[230:233], v86, v194, v[230:233]
	v_mfma_f32_16x16x4_f32 v[230:233], v87, v195, v[230:233]
	s_nop 7
	s_nop 2
	v_sub_f32_e32 v230, v196, v230
	v_sub_f32_e32 v231, v197, v231
	v_sub_f32_e32 v232, v198, v232
	v_sub_f32_e32 v233, v199, v233
	s_nop 1
	v_mfma_f32_16x16x4_f32 v[196:199], v58, v230, 0
	v_mfma_f32_16x16x4_f32 v[196:199], v59, v231, v[196:199]
	v_mfma_f32_16x16x4_f32 v[196:199], v60, v232, v[196:199]
	v_mfma_f32_16x16x4_f32 v[196:199], v61, v233, v[196:199]
	s_nop 7
	s_nop 2
	v_mfma_f32_16x16x4_f32 v[230:233], v88, v192, 0
	v_mfma_f32_16x16x4_f32 v[230:233], v89, v193, v[230:233]
	v_mfma_f32_16x16x4_f32 v[230:233], v90, v194, v[230:233]
	v_mfma_f32_16x16x4_f32 v[230:233], v91, v195, v[230:233]
	v_mfma_f32_16x16x4_f32 v[230:233], v92, v196, v[230:233]
	v_mfma_f32_16x16x4_f32 v[230:233], v93, v197, v[230:233]
	v_mfma_f32_16x16x4_f32 v[230:233], v94, v198, v[230:233]
	v_mfma_f32_16x16x4_f32 v[230:233], v95, v199, v[230:233]
	s_nop 7
	s_nop 2
	v_sub_f32_e32 v230, v200, v230
	v_sub_f32_e32 v231, v201, v231
	v_sub_f32_e32 v232, v202, v232
	v_sub_f32_e32 v233, v203, v233
	s_nop 1
	v_mfma_f32_16x16x4_f32 v[200:203], v234, v230, 0
	v_mfma_f32_16x16x4_f32 v[200:203], v235, v231, v[200:203]
	v_mfma_f32_16x16x4_f32 v[200:203], v236, v232, v[200:203]
	v_mfma_f32_16x16x4_f32 v[200:203], v237, v233, v[200:203]
	s_nop 7
	s_nop 2
	v_mfma_f32_16x16x4_f32 v[230:233], v96, v192, 0
	v_mfma_f32_16x16x4_f32 v[230:233], v97, v193, v[230:233]
	v_mfma_f32_16x16x4_f32 v[230:233], v98, v194, v[230:233]
	v_mfma_f32_16x16x4_f32 v[230:233], v99, v195, v[230:233]
	v_mfma_f32_16x16x4_f32 v[230:233], v100, v196, v[230:233]
	v_mfma_f32_16x16x4_f32 v[230:233], v101, v197, v[230:233]
	v_mfma_f32_16x16x4_f32 v[230:233], v102, v198, v[230:233]
	v_mfma_f32_16x16x4_f32 v[230:233], v103, v199, v[230:233]
	v_mfma_f32_16x16x4_f32 v[230:233], v104, v200, v[230:233]
	v_mfma_f32_16x16x4_f32 v[230:233], v105, v201, v[230:233]
	v_mfma_f32_16x16x4_f32 v[230:233], v106, v202, v[230:233]
	v_mfma_f32_16x16x4_f32 v[230:233], v107, v203, v[230:233]
	s_nop 7
	s_nop 2
	v_sub_f32_e32 v230, v204, v230
	v_sub_f32_e32 v231, v205, v231
	v_sub_f32_e32 v232, v206, v232
	v_sub_f32_e32 v233, v207, v233
	s_nop 1
	v_mfma_f32_16x16x4_f32 v[204:207], v238, v230, 0
	v_mfma_f32_16x16x4_f32 v[204:207], v239, v231, v[204:207]
	v_mfma_f32_16x16x4_f32 v[204:207], v240, v232, v[204:207]
	v_mfma_f32_16x16x4_f32 v[204:207], v241, v233, v[204:207]
	s_nop 7
	s_nop 2
	ds_write_b32 v187, v192 offset:0
	ds_write_b32 v187, v193 offset:260
	ds_write_b32 v187, v194 offset:520
	ds_write_b32 v187, v195 offset:780
	ds_write_b32 v187, v196 offset:4160
	ds_write_b32 v187, v197 offset:4420
	ds_write_b32 v187, v198 offset:4680
	ds_write_b32 v187, v199 offset:4940
	ds_write_b32 v187, v200 offset:8320
	ds_write_b32 v187, v201 offset:8580
	ds_write_b32 v187, v202 offset:8840
	ds_write_b32 v187, v203 offset:9100
	ds_write_b32 v187, v204 offset:12480
	ds_write_b32 v187, v205 offset:12740
	ds_write_b32 v187, v206 offset:13000
	ds_write_b32 v187, v207 offset:13260
	ds_read_b32 v192, v187 offset:64
	ds_read_b32 v193, v187 offset:324
	ds_read_b32 v194, v187 offset:584
	ds_read_b32 v195, v187 offset:844
	ds_read_b32 v196, v187 offset:4224
	ds_read_b32 v197, v187 offset:4484
	ds_read_b32 v198, v187 offset:4744
	ds_read_b32 v199, v187 offset:5004
	ds_read_b32 v200, v187 offset:8384
	ds_read_b32 v201, v187 offset:8644
	ds_read_b32 v202, v187 offset:8904
	ds_read_b32 v203, v187 offset:9164
	ds_read_b32 v204, v187 offset:12544
	ds_read_b32 v205, v187 offset:12804
	ds_read_b32 v206, v187 offset:13064
	ds_read_b32 v207, v187 offset:13324
	s_waitcnt lgkmcnt(0)
; DI void phase_gdn_prep(const Params& p, int l, char* smem) {
;     ...
;         for (int rb = 0; rb < 4; ++rb) {
;             if (rb > 0) {
;                 const int j = tid & 127, rh = tid >> 7;
;                 float* X = (j < 64) ? sv : sk; const int col = j & 63;
;                 const int r0 = rb * 16 + rh * 8;
;                 float a[8];
; #pragma unroll
;                 for (int i = 0; i < 8; ++i) a[i] = 0.f;
;                 for (int s4 = 0; s4 < rb * 16; s4 += 4) {
;                     const float x0 = X[(s4 + 0) * 65 + col], x1 = X[(s4 + 1) * 65 + col], x2 = X[(s4 + 2) * 65 + col], x3 = X[(s4 + 3) * 65 + col];
; #pragma unroll
;                     for (int i = 0; i < 8; ++i) {
;                         const f32x4 lv = *(const f32x4*)(sL + (r0 + i) * 64 + s4);
;                         a[i] += lv[0] * x0 + lv[1] * x1 + lv[2] * x2 + lv[3] * x3;
;                     }
;                 }
; #pragma unroll
;                 for (int i = 0; i < 8; ++i) X[(r0 + i) * 65 + col] -= a[i];
;                 __syncthreads();
;             }
;             if (tid < 128) {
;                 float* X = (tid < 64) ? sv : sk; const int col = tid & 63;
;                 float x[16];
; #pragma unroll
;                 for (int i = 0; i < 16; ++i) x[i] = X[(rb * 16 + i) * 65 + col];
; #pragma unroll
;                 for (int i = 1; i < 16; ++i) {
;                     const float* Lr = sL + (rb * 16 + i) * 64 + rb * 16;
;                     float acc = x[i];
; #pragma unroll
;                     for (int s2 = 0; s2 < i; ++s2) acc -= Lr[s2] * x[s2];
;                     x[i] = acc;
;                 }
; #pragma unroll
;                 for (int i = 1; i < 16; ++i) X[(rb * 16 + i) * 65 + col] = x[i];
;             }
;             __syncthreads();
;         }
	v_mfma_f32_16x16x4_f32 v[230:233], v36, v192, 0
	v_mfma_f32_16x16x4_f32 v[230:233], v37, v193, v[230:233]
	v_mfma_f32_16x16x4_f32 v[230:233], v38, v194, v[230:233]
	v_mfma_f32_16x16x4_f32 v[230:233], v39, v195, v[230:233]
	s_nop 7
	s_nop 2
	v_mov_b32_e32 v192, v230
	v_mov_b32_e32 v193, v231
	v_mov_b32_e32 v194, v232
	v_mov_b32_e32 v195, v233
	s_nop 7
	s_nop 2
	v_mfma_f32_16x16x4_f32 v[230:233], v84, v192, 0
	v_mfma_f32_16x16x4_f32 v[230:233], v85, v193, v[230:233]
	v_mfma_f32_16x16x4_f32 v[230:233], v86, v194, v[230:233]
	v_mfma_f32_16x16x4_f32 v[230:233], v87, v195, v[230:233]
	s_nop 7
	s_nop 2
	v_sub_f32_e32 v230, v196, v230
	v_sub_f32_e32 v231, v197, v231
	v_sub_f32_e32 v232, v198, v232
	v_sub_f32_e32 v233, v199, v233
	s_nop 1
	v_mfma_f32_16x16x4_f32 v[196:199], v58, v230, 0
	v_mfma_f32_16x16x4_f32 v[196:199], v59, v231, v[196:199]
	v_mfma_f32_16x16x4_f32 v[196:199], v60, v232, v[196:199]
	v_mfma_f32_16x16x4_f32 v[196:199], v61, v233, v[196:199]
	s_nop 7
	s_nop 2
	v_mfma_f32_16x16x4_f32 v[230:233], v88, v192, 0
	v_mfma_f32_16x16x4_f32 v[230:233], v89, v193, v[230:233]
	v_mfma_f32_16x16x4_f32 v[230:233], v90, v194, v[230:233]
	v_mfma_f32_16x16x4_f32 v[230:233], v91, v195, v[230:233]
	v_mfma_f32_16x16x4_f32 v[230:233], v92, v196, v[230:233]
	v_mfma_f32_16x16x4_f32 v[230:233], v93, v197, v[230:233]
	v_mfma_f32_16x16x4_f32 v[230:233], v94, v198, v[230:233]
	v_mfma_f32_16x16x4_f32 v[230:233], v95, v199, v[230:233]
	s_nop 7
	s_nop 2
	v_sub_f32_e32 v230, v200, v230
	v_sub_f32_e32 v231, v201, v231
	v_sub_f32_e32 v232, v202, v232
	v_sub_f32_e32 v233, v203, v233
	s_nop 1
	v_mfma_f32_16x16x4_f32 v[200:203], v234, v230, 0
	v_mfma_f32_16x16x4_f32 v[200:203], v235, v231, v[200:203]
	v_mfma_f32_16x16x4_f32 v[200:203], v236, v232, v[200:203]
	v_mfma_f32_16x16x4_f32 v[200:203], v237, v233, v[200:203]
	s_nop 7
	s_nop 2
	v_mfma_f32_16x16x4_f32 v[230:233], v96, v192, 0
	v_mfma_f32_16x16x4_f32 v[230:233], v97, v193, v[230:233]
	v_mfma_f32_16x16x4_f32 v[230:233], v98, v194, v[230:233]
	v_mfma_f32_16x16x4_f32 v[230:233], v99, v195, v[230:233]
	v_mfma_f32_16x16x4_f32 v[230:233], v100, v196, v[230:233]
	v_mfma_f32_16x16x4_f32 v[230:233], v101, v197, v[230:233]
	v_mfma_f32_16x16x4_f32 v[230:233], v102, v198, v[230:233]
	v_mfma_f32_16x16x4_f32 v[230:233], v103, v199, v[230:233]
	v_mfma_f32_16x16x4_f32 v[230:233], v104, v200, v[230:233]
	v_mfma_f32_16x16x4_f32 v[230:233], v105, v201, v[230:233]
	v_mfma_f32_16x16x4_f32 v[230:233], v106, v202, v[230:233]
	v_mfma_f32_16x16x4_f32 v[230:233], v107, v203, v[230:233]
	s_nop 7
	s_nop 2
	v_sub_f32_e32 v230, v204, v230
	v_sub_f32_e32 v231, v205, v231
	v_sub_f32_e32 v232, v206, v232
	v_sub_f32_e32 v233, v207, v233
	s_nop 1
	v_mfma_f32_16x16x4_f32 v[204:207], v238, v230, 0
	v_mfma_f32_16x16x4_f32 v[204:207], v239, v231, v[204:207]
	v_mfma_f32_16x16x4_f32 v[204:207], v240, v232, v[204:207]
	v_mfma_f32_16x16x4_f32 v[204:207], v241, v233, v[204:207]
	s_nop 7
	s_nop 2
	ds_write_b32 v187, v192 offset:64
	ds_write_b32 v187, v193 offset:324
	ds_write_b32 v187, v194 offset:584
	ds_write_b32 v187, v195 offset:844
	ds_write_b32 v187, v196 offset:4224
	ds_write_b32 v187, v197 offset:4484
	ds_write_b32 v187, v198 offset:4744
	ds_write_b32 v187, v199 offset:5004
	ds_write_b32 v187, v200 offset:8384
	ds_write_b32 v187, v201 offset:8644
	ds_write_b32 v187, v202 offset:8904
	ds_write_b32 v187, v203 offset:9164
	ds_write_b32 v187, v204 offset:12544
	ds_write_b32 v187, v205 offset:12804
	ds_write_b32 v187, v206 offset:13064
	ds_write_b32 v187, v207 offset:13324
	s_waitcnt lgkmcnt(0)
	s_barrier
	s_branch .LBB0_263
